# nt hint on the read-once V-row LDS-DMA loads of the ret prompt scan
# baseline (speedup 1.0000x reference)
; #define LAS __attribute__((address_space(3)))
; #define MFMA32(a, b, c) __builtin_amdgcn_mfma_f32_32x32x16_bf16((a), (b), (c), 0, 0, 0)
; #define RET_DMA_B(n) do { const unsigned char* g_ = gblk + (size_t)(n) * ROP_STRIDE; RET_CP(32768, 40960, 4); } while (0)
; DI void ret_scan_prompt(const Params& p, int item, unsigned char* smem) {
;     ...
;         RET_DMA_B(n);
;         f32x16 O[2];
; #pragma unroll
;         for (int rt = 0; rt < 2; ++rt)
; #pragma unroll
;             for (int i = 0; i < 16; ++i) O[rt][i] = 0.f;
;         const LAS unsigned short* vcol = (const LAS unsigned short*)(lds + 73728 + (n & 1) * 32768 + (wid * 32 + l31) * 2 + hh * (8 * 512));
;     ...
; #pragma unroll
;         for (int t = 0; t < 8; ++t)
; #pragma unroll
;             for (int s2 = 0; s2 < 2; ++s2) {
;                 const bf16x8 sb = packB(S[t], s2);
; #pragma unroll
;                 for (int rt = 0; rt < 2; ++rt) O[rt] = MFMA32(LDSV((rt * 16 + 2 * t + s2) * 1024), sb, O[rt]);
;                 if (s2 == 1 && (t & 1)) __builtin_amdgcn_sched_barrier(0);
;             }
.LBB0_1376:
	v_lshl_add_u64 v[188:189], s[78:79], 0, v[176:177]
	v_lshl_add_u64 v[130:131], v[188:189], 0, s[8:9]
	s_add_i32 m0, s55, 0xa000
	v_lshl_add_u64 v[190:191], s[78:79], 0, v[178:179]
	global_load_lds_dwordx4 v[130:131], off
	v_lshl_add_u64 v[130:131], v[190:191], 0, s[8:9]
	s_add_i32 m0, s55, 0xc000
	v_lshl_add_u64 v[192:193], s[78:79], 0, v[180:181]
	global_load_lds_dwordx4 v[130:131], off
	v_lshl_add_u64 v[130:131], v[192:193], 0, s[8:9]
	s_add_i32 m0, s55, 0xe000
	v_lshl_add_u64 v[194:195], s[78:79], 0, v[182:183]
	s_add_i32 s23, s22, 0
	global_load_lds_dwordx4 v[130:131], off
	v_lshl_add_u64 v[130:131], v[194:195], 0, s[8:9]
	s_add_i32 m0, s23, 0xa000
	v_cvt_pk_bf16_f32 v134, v114, v115
	global_load_lds_dwordx4 v[130:131], off
	ds_read_b128 v[130:133], v204
	ds_read_b128 v[214:217], v204 offset:1024
	v_cvt_pk_bf16_f32 v135, v116, v117
	v_cvt_pk_bf16_f32 v136, v118, v119
	v_cvt_pk_bf16_f32 v137, v120, v121
	v_cvt_pk_bf16_f32 v222, v122, v123
	v_cvt_pk_bf16_f32 v223, v124, v125
	s_waitcnt lgkmcnt(0)
	v_mfma_f32_32x32x16_bf16 v[146:161], v[130:133], v[134:137], 0
	ds_read_b128 v[130:133], v204 offset:16384
	ds_read_b128 v[218:221], v204 offset:17408
	v_cvt_pk_bf16_f32 v224, v126, v127
	v_cvt_pk_bf16_f32 v225, v128, v129
	s_add_i32 s23, s21, 0xffff8000
	s_and_b32 s23, s23, 0x8000
	s_waitcnt lgkmcnt(0)
	v_mfma_f32_32x32x16_bf16 v[130:145], v[130:133], v[134:137], 0
	v_mfma_f32_32x32x16_bf16 v[146:161], v[214:217], v[222:225], v[146:161]
	ds_read_b128 v[214:217], v204 offset:2048
	v_mfma_f32_32x32x16_bf16 v[130:145], v[218:221], v[222:225], v[130:145]
	v_cvt_pk_bf16_f32 v218, v98, v99
	v_cvt_pk_bf16_f32 v219, v100, v101
	v_cvt_pk_bf16_f32 v220, v102, v103
	v_cvt_pk_bf16_f32 v221, v104, v105
	ds_read_b128 v[222:225], v204 offset:3072
	s_waitcnt lgkmcnt(0)
	v_mfma_f32_32x32x16_bf16 v[146:161], v[214:217], v[218:221], v[146:161]
	ds_read_b128 v[214:217], v204 offset:18432
	ds_read_b128 v[226:229], v204 offset:19456
	s_waitcnt lgkmcnt(0)
	v_mfma_f32_32x32x16_bf16 v[130:145], v[214:217], v[218:221], v[130:145]
	v_cvt_pk_bf16_f32 v214, v106, v107
	v_cvt_pk_bf16_f32 v215, v108, v109
	v_cvt_pk_bf16_f32 v216, v110, v111
	v_cvt_pk_bf16_f32 v217, v112, v113
	s_nop 1
	v_mfma_f32_32x32x16_bf16 v[146:161], v[222:225], v[214:217], v[146:161]
	v_mfma_f32_32x32x16_bf16 v[130:145], v[226:229], v[214:217], v[130:145]
	ds_read_b128 v[214:217], v204 offset:4096
	ds_read_b128 v[222:225], v204 offset:5120
	v_cvt_pk_bf16_f32 v218, v82, v83
	v_cvt_pk_bf16_f32 v219, v84, v85
	v_cvt_pk_bf16_f32 v220, v86, v87
	v_cvt_pk_bf16_f32 v221, v88, v89
	s_waitcnt lgkmcnt(0)
	s_nop 0
	v_mfma_f32_32x32x16_bf16 v[146:161], v[214:217], v[218:221], v[146:161]
	ds_read_b128 v[214:217], v204 offset:20480
	ds_read_b128 v[226:229], v204 offset:21504
	s_waitcnt lgkmcnt(0)
	v_mfma_f32_32x32x16_bf16 v[130:145], v[214:217], v[218:221], v[130:145]
	v_cvt_pk_bf16_f32 v214, v90, v91
	v_cvt_pk_bf16_f32 v215, v92, v93
	v_cvt_pk_bf16_f32 v216, v94, v95
	v_cvt_pk_bf16_f32 v217, v96, v97
	v_cvt_pk_bf16_f32 v218, v50, v51
	v_cvt_pk_bf16_f32 v219, v52, v53
	v_cvt_pk_bf16_f32 v220, v54, v55
	v_mfma_f32_32x32x16_bf16 v[146:161], v[222:225], v[214:217], v[146:161]
	v_cvt_pk_bf16_f32 v221, v56, v57
	ds_read_b128 v[222:225], v204 offset:7168
	v_mfma_f32_32x32x16_bf16 v[130:145], v[226:229], v[214:217], v[130:145]
	ds_read_b128 v[214:217], v204 offset:6144
	s_waitcnt lgkmcnt(0)
	v_mfma_f32_32x32x16_bf16 v[146:161], v[214:217], v[218:221], v[146:161]
	ds_read_b128 v[214:217], v204 offset:22528
	ds_read_b128 v[226:229], v204 offset:23552
	s_waitcnt lgkmcnt(0)
	v_mfma_f32_32x32x16_bf16 v[130:145], v[214:217], v[218:221], v[130:145]
	v_cvt_pk_bf16_f32 v214, v58, v59
	v_cvt_pk_bf16_f32 v215, v60, v61
	v_cvt_pk_bf16_f32 v216, v62, v63
	v_cvt_pk_bf16_f32 v217, v64, v65
	s_nop 1
	v_mfma_f32_32x32x16_bf16 v[146:161], v[222:225], v[214:217], v[146:161]
	v_mfma_f32_32x32x16_bf16 v[130:145], v[226:229], v[214:217], v[130:145]
	ds_read_b128 v[214:217], v204 offset:8192
	ds_read_b128 v[222:225], v204 offset:9216
	v_cvt_pk_bf16_f32 v218, v66, v67
	v_cvt_pk_bf16_f32 v219, v68, v69
	v_cvt_pk_bf16_f32 v220, v70, v71
	v_cvt_pk_bf16_f32 v221, v72, v73
	s_waitcnt lgkmcnt(0)
	s_nop 0
	v_mfma_f32_32x32x16_bf16 v[146:161], v[214:217], v[218:221], v[146:161]
	ds_read_b128 v[214:217], v204 offset:24576
	ds_read_b128 v[226:229], v204 offset:25600
	s_waitcnt lgkmcnt(0)
	v_mfma_f32_32x32x16_bf16 v[130:145], v[214:217], v[218:221], v[130:145]
	v_cvt_pk_bf16_f32 v214, v74, v75
	v_cvt_pk_bf16_f32 v215, v76, v77
	v_cvt_pk_bf16_f32 v216, v78, v79
	v_cvt_pk_bf16_f32 v217, v80, v81
	v_cvt_pk_bf16_f32 v218, v34, v35
	v_cvt_pk_bf16_f32 v219, v36, v37
	v_cvt_pk_bf16_f32 v220, v38, v39
	v_mfma_f32_32x32x16_bf16 v[146:161], v[222:225], v[214:217], v[146:161]
	v_cvt_pk_bf16_f32 v221, v40, v41
	ds_read_b128 v[222:225], v204 offset:11264
	v_mfma_f32_32x32x16_bf16 v[130:145], v[226:229], v[214:217], v[130:145]
	ds_read_b128 v[214:217], v204 offset:10240
	s_waitcnt lgkmcnt(0)
	v_mfma_f32_32x32x16_bf16 v[146:161], v[214:217], v[218:221], v[146:161]
	ds_read_b128 v[214:217], v204 offset:26624
	ds_read_b128 v[226:229], v204 offset:27648
	s_waitcnt lgkmcnt(0)
	v_mfma_f32_32x32x16_bf16 v[130:145], v[214:217], v[218:221], v[130:145]
	v_cvt_pk_bf16_f32 v214, v42, v43
	v_cvt_pk_bf16_f32 v215, v44, v45
	v_cvt_pk_bf16_f32 v216, v46, v47
	v_cvt_pk_bf16_f32 v217, v48, v49
	s_nop 1
	v_mfma_f32_32x32x16_bf16 v[146:161], v[222:225], v[214:217], v[146:161]
	v_mfma_f32_32x32x16_bf16 v[130:145], v[226:229], v[214:217], v[130:145]
	ds_read_b128 v[214:217], v204 offset:12288
	ds_read_b128 v[222:225], v204 offset:13312
	v_cvt_pk_bf16_f32 v218, v18, v19
	v_cvt_pk_bf16_f32 v219, v20, v21
	v_cvt_pk_bf16_f32 v220, v22, v23
	v_cvt_pk_bf16_f32 v221, v24, v25
	s_waitcnt lgkmcnt(0)
; #define MFMA32(a, b, c) __builtin_amdgcn_mfma_f32_32x32x16_bf16((a), (b), (c), 0, 0, 0)
; DI void ret_scan_prompt(const Params& p, int item, unsigned char* smem) {
;     ...
; #pragma unroll
;         for (int t = 0; t < 8; ++t)
; #pragma unroll
;             for (int s2 = 0; s2 < 2; ++s2) {
;                 const bf16x8 sb = packB(S[t], s2);
; #pragma unroll
;                 for (int rt = 0; rt < 2; ++rt) O[rt] = MFMA32(LDSV((rt * 16 + 2 * t + s2) * 1024), sb, O[rt]);
;                 if (s2 == 1 && (t & 1)) __builtin_amdgcn_sched_barrier(0);
;             }
; #pragma unroll
;         for (int kc = 0; kc < 4; ++kc) { const bf16x8 vb = RET_VFRAG(kc);
; #pragma unroll
;             for (int rt = (kc >> 1); rt < 2; ++rt) O[rt] = MFMA32(LDSV(32768 + (rt * 4 + kc) * 1024), vb, O[rt]); }
	s_nop 0
	v_mfma_f32_32x32x16_bf16 v[146:161], v[214:217], v[218:221], v[146:161]
	ds_read_b128 v[214:217], v204 offset:28672
	ds_read_b128 v[226:229], v204 offset:29696
	s_waitcnt lgkmcnt(0)
	v_mfma_f32_32x32x16_bf16 v[130:145], v[214:217], v[218:221], v[130:145]
	v_cvt_pk_bf16_f32 v214, v26, v27
	v_cvt_pk_bf16_f32 v215, v28, v29
	v_cvt_pk_bf16_f32 v216, v30, v31
	v_cvt_pk_bf16_f32 v217, v32, v33
	v_cvt_pk_bf16_f32 v218, v2, v3
	v_cvt_pk_bf16_f32 v219, v4, v5
	v_cvt_pk_bf16_f32 v220, v6, v7
	v_mfma_f32_32x32x16_bf16 v[146:161], v[222:225], v[214:217], v[146:161]
	v_cvt_pk_bf16_f32 v221, v8, v9
	ds_read_b128 v[222:225], v204 offset:15360
	v_mfma_f32_32x32x16_bf16 v[130:145], v[226:229], v[214:217], v[130:145]
	ds_read_b128 v[214:217], v204 offset:14336
	s_waitcnt lgkmcnt(0)
	v_mfma_f32_32x32x16_bf16 v[146:161], v[214:217], v[218:221], v[146:161]
	ds_read_b128 v[214:217], v204 offset:30720
	ds_read_b128 v[226:229], v204 offset:31744
	s_waitcnt lgkmcnt(0)
	v_mfma_f32_32x32x16_bf16 v[130:145], v[214:217], v[218:221], v[130:145]
	v_cvt_pk_bf16_f32 v214, v10, v11
	v_cvt_pk_bf16_f32 v215, v12, v13
	v_cvt_pk_bf16_f32 v216, v14, v15
	v_cvt_pk_bf16_f32 v217, v16, v17
	s_nop 1
	v_mfma_f32_32x32x16_bf16 v[146:161], v[222:225], v[214:217], v[146:161]
	v_mfma_f32_32x32x16_bf16 v[130:145], v[226:229], v[214:217], v[130:145]
	v_add_u32_e32 v168, s23, v205
	ds_read_b128 v[214:217], v204 offset:32768
	ds_read_u16 v171, v168 offset:512
	ds_read_u16 v221, v168 offset:3072
	ds_read_u16 v220, v168 offset:2048
	ds_read_u16 v219, v168 offset:1024
	ds_read_u16 v218, v168
	ds_read_u16 v222, v168 offset:1536
	ds_read_u16 v223, v168 offset:2560
	ds_read_u16 v224, v168 offset:3584
	s_mov_b32 s23, 0x3c82000
	s_waitcnt lgkmcnt(0)
	v_lshl_or_b32 v218, v171, 16, v218
	v_lshl_or_b32 v219, v222, 16, v219
	v_lshl_or_b32 v220, v223, 16, v220
	v_lshl_or_b32 v221, v224, 16, v221
	ds_read_b128 v[222:225], v204 offset:33792
	s_cmp_eq_u32 s21, 0x100000
	v_mfma_f32_32x32x16_bf16 v[146:161], v[214:217], v[218:221], v[146:161]
	ds_read_b128 v[214:217], v204 offset:36864
	ds_read_b128 v[226:229], v204 offset:37888
	s_waitcnt lgkmcnt(0)
	v_mfma_f32_32x32x16_bf16 v[130:145], v[214:217], v[218:221], v[130:145]
	ds_read_u16 v171, v168 offset:8704
	ds_read_u16 v217, v168 offset:11264
	ds_read_u16 v216, v168 offset:10240
	ds_read_u16 v215, v168 offset:9216
	ds_read_u16 v214, v168 offset:8192
	ds_read_u16 v218, v168 offset:9728
	ds_read_u16 v219, v168 offset:10752
	ds_read_u16 v220, v168 offset:11776
	s_waitcnt lgkmcnt(0)
	v_lshl_or_b32 v214, v171, 16, v214
	v_lshl_or_b32 v215, v218, 16, v215
	v_lshl_or_b32 v216, v219, 16, v216
	v_lshl_or_b32 v217, v220, 16, v217
	s_nop 1
	v_mfma_f32_32x32x16_bf16 v[130:145], v[226:229], v[214:217], v[130:145]
	v_mfma_f32_32x32x16_bf16 v[146:161], v[222:225], v[214:217], v[146:161]
	ds_read_b128 v[214:217], v204 offset:38912
	ds_read_u16 v171, v168 offset:16896
	ds_read_u16 v221, v168 offset:19456
	ds_read_u16 v220, v168 offset:18432
	ds_read_u16 v219, v168 offset:17408
	ds_read_u16 v218, v168 offset:16384
	ds_read_u16 v222, v168 offset:17920
	ds_read_u16 v223, v168 offset:18944
	ds_read_u16 v224, v168 offset:19968
	s_waitcnt lgkmcnt(0)
	v_lshl_or_b32 v218, v171, 16, v218
	v_lshl_or_b32 v219, v222, 16, v219
	v_lshl_or_b32 v220, v223, 16, v220
	v_lshl_or_b32 v221, v224, 16, v221
	ds_read_b128 v[222:225], v204 offset:39936
	v_cvt_pk_bf16_f32 v146, v146, s0
	v_mfma_f32_32x32x16_bf16 v[130:145], v[214:217], v[218:221], v[130:145]
	ds_read_u16 v171, v168 offset:25088
	ds_read_u16 v217, v168 offset:27648
	ds_read_u16 v216, v168 offset:26624
	ds_read_u16 v215, v168 offset:25600
	ds_read_u16 v214, v168 offset:24576
	ds_read_u16 v218, v168 offset:26112
	ds_read_u16 v219, v168 offset:27136
	ds_read_u16 v220, v168 offset:28160
	v_cvt_pk_bf16_f32 v148, v148, s0
	s_waitcnt lgkmcnt(0)
; DI bf16_t f2bf(float a) { return (bf16_t)(pk_bf16(a, 0.f) & 0xffffu); }
; #define MFMA32(a, b, c) __builtin_amdgcn_mfma_f32_32x32x16_bf16((a), (b), (c), 0, 0, 0)
; DI int crow(int i, int hh) { return (i & 3) + 8 * (i >> 2) + 4 * hh; }
; DI void lds_barrier() { asm volatile("s_waitcnt lgkmcnt(0)" ::: "memory"); __builtin_amdgcn_s_barrier(); asm volatile("" ::: "memory"); }
; #define RET_DMA_A(n) do { const unsigned char* g_ = gblk + (size_t)(n) * ROP_STRIDE; RET_CP(0, 0, 4); RET_CP(65536, 32768, 1); RET_DMA_V(n); } while (0)
; DI void ret_scan_prompt(const Params& p, int item, unsigned char* smem) {
;     ...
;         for (int kc = 0; kc < 4; ++kc) { const bf16x8 vb = RET_VFRAG(kc);
; #pragma unroll
;             for (int rt = (kc >> 1); rt < 2; ++rt) O[rt] = MFMA32(LDSV(32768 + (rt * 4 + kc) * 1024), vb, O[rt]); }
;         const size_t tok0 = (size_t)b * 2048 + n * 64;
; #pragma unroll
;         for (int rt = 0; rt < 2; ++rt)
; #pragma unroll
;             for (int i = 0; i < 16; ++i) oraw[(tok0 + 32 * rt + crow(i, hh)) * 2048 + h * 512 + 32 * s + l31] = f2bf(O[rt][i]);
;         asm volatile("s_waitcnt vmcnt(0)" ::: "memory"); lds_barrier();
;         if (n + 1 < 32) RET_DMA_A(n + 1);
	v_lshl_or_b32 v214, v171, 16, v214
	v_lshl_or_b32 v215, v218, 16, v215
	v_lshl_or_b32 v216, v219, 16, v216
	v_lshl_or_b32 v217, v220, 16, v217
	v_cvt_pk_bf16_f32 v171, v147, s0
	v_cvt_pk_bf16_f32 v150, v150, s0
	v_mfma_f32_32x32x16_bf16 v[130:145], v[222:225], v[214:217], v[130:145]
	v_lshl_add_u64 v[214:215], s[78:79], 0, v[186:187]
	global_store_short v[214:215], v146, off
	v_lshl_add_u64 v[146:147], s[78:79], 0, v[184:185]
	v_add_co_u32_e32 v214, vcc, s23, v146
	s_mov_b32 s23, 0x3c83000
	s_nop 0
	v_addc_co_u32_e32 v215, vcc, 0, v147, vcc
	global_store_short v[214:215], v148, off
	v_add_co_u32_e32 v148, vcc, s23, v146
	global_store_short v[214:215], v171, off offset:-4096
	v_cvt_pk_bf16_f32 v171, v149, s0
	v_addc_co_u32_e32 v149, vcc, 0, v147, vcc
	s_mov_b32 s23, 0x3c89000
	global_store_short v[148:149], v171, off
	v_add_co_u32_e32 v148, vcc, s23, v146
	s_mov_b32 s23, 0x3c8b000
	s_nop 0
	v_addc_co_u32_e32 v149, vcc, 0, v147, vcc
	global_store_short v[148:149], v150, off offset:-4096
	v_cvt_pk_bf16_f32 v150, v151, s0
	global_store_short v[148:149], v150, off
	v_add_co_u32_e32 v148, vcc, s23, v146
	v_cvt_pk_bf16_f32 v150, v152, s0
	s_nop 0
	v_addc_co_u32_e32 v149, vcc, 0, v147, vcc
	global_store_short v[148:149], v150, off offset:-4096
	v_cvt_pk_bf16_f32 v150, v153, s0
	s_mov_b32 s23, 0x3c91000
	global_store_short v[148:149], v150, off
	v_add_co_u32_e32 v148, vcc, s23, v146
	v_cvt_pk_bf16_f32 v150, v154, s0
	s_nop 0
	v_addc_co_u32_e32 v149, vcc, 0, v147, vcc
	global_store_short v[148:149], v150, off offset:-4096
	v_cvt_pk_bf16_f32 v150, v155, s0
	s_mov_b32 s23, 0x3c93000
	global_store_short v[148:149], v150, off
	v_add_co_u32_e32 v148, vcc, s23, v146
	v_cvt_pk_bf16_f32 v150, v156, s0
	s_nop 0
	v_addc_co_u32_e32 v149, vcc, 0, v147, vcc
	global_store_short v[148:149], v150, off offset:-4096
	v_cvt_pk_bf16_f32 v150, v157, s0
	s_mov_b32 s23, 0x3c99000
	global_store_short v[148:149], v150, off
	v_add_co_u32_e32 v148, vcc, s23, v146
	v_cvt_pk_bf16_f32 v150, v158, s0
	s_nop 0
	v_addc_co_u32_e32 v149, vcc, 0, v147, vcc
	global_store_short v[148:149], v150, off offset:-4096
	v_cvt_pk_bf16_f32 v150, v159, s0
	s_mov_b32 s23, 0x3c9b000
	global_store_short v[148:149], v150, off
	v_add_co_u32_e32 v148, vcc, s23, v146
	v_cvt_pk_bf16_f32 v150, v160, s0
	s_nop 0
	v_addc_co_u32_e32 v149, vcc, 0, v147, vcc
	global_store_short v[148:149], v150, off offset:-4096
	v_cvt_pk_bf16_f32 v150, v161, s0
	s_mov_b32 s23, 0x3ca1000
	global_store_short v[148:149], v150, off
	v_add_co_u32_e32 v148, vcc, s23, v146
	v_cvt_pk_bf16_f32 v130, v130, s0
	s_nop 0
	v_addc_co_u32_e32 v149, vcc, 0, v147, vcc
	global_store_short v[148:149], v130, off offset:-4096
	v_cvt_pk_bf16_f32 v130, v131, s0
	s_mov_b32 s23, 0x3ca3000
	global_store_short v[148:149], v130, off
	v_add_co_u32_e32 v130, vcc, s23, v146
	v_cvt_pk_bf16_f32 v132, v132, s0
	s_nop 0
	v_addc_co_u32_e32 v131, vcc, 0, v147, vcc
	global_store_short v[130:131], v132, off offset:-4096
	v_cvt_pk_bf16_f32 v132, v133, s0
	s_mov_b32 s23, 0x3ca9000
	global_store_short v[130:131], v132, off
	v_add_co_u32_e32 v130, vcc, s23, v146
	v_cvt_pk_bf16_f32 v132, v134, s0
	s_nop 0
	v_addc_co_u32_e32 v131, vcc, 0, v147, vcc
	global_store_short v[130:131], v132, off offset:-4096
	v_cvt_pk_bf16_f32 v132, v135, s0
	s_mov_b32 s23, 0x3cab000
	global_store_short v[130:131], v132, off
	v_add_co_u32_e32 v130, vcc, s23, v146
	v_cvt_pk_bf16_f32 v132, v136, s0
	s_nop 0
	v_addc_co_u32_e32 v131, vcc, 0, v147, vcc
	global_store_short v[130:131], v132, off offset:-4096
	v_cvt_pk_bf16_f32 v132, v137, s0
	s_mov_b32 s23, 0x3cb1000
	global_store_short v[130:131], v132, off
	v_add_co_u32_e32 v130, vcc, s23, v146
	v_cvt_pk_bf16_f32 v132, v138, s0
	s_nop 0
	v_addc_co_u32_e32 v131, vcc, 0, v147, vcc
	global_store_short v[130:131], v132, off offset:-4096
	v_cvt_pk_bf16_f32 v132, v139, s0
	s_mov_b32 s23, 0x3cb3000
	global_store_short v[130:131], v132, off
	v_add_co_u32_e32 v130, vcc, s23, v146
	v_cvt_pk_bf16_f32 v132, v140, s0
	s_nop 0
	v_addc_co_u32_e32 v131, vcc, 0, v147, vcc
	global_store_short v[130:131], v132, off offset:-4096
	v_cvt_pk_bf16_f32 v132, v141, s0
	s_mov_b32 s23, 0x3cb9000
	global_store_short v[130:131], v132, off
	v_add_co_u32_e32 v130, vcc, s23, v146
	v_cvt_pk_bf16_f32 v132, v142, s0
	s_nop 0
	v_addc_co_u32_e32 v131, vcc, 0, v147, vcc
	global_store_short v[130:131], v132, off offset:-4096
	v_cvt_pk_bf16_f32 v132, v143, s0
	global_store_short v[130:131], v132, off
	v_add_co_u32_e32 v130, vcc, 0x3cba000, v146
	v_cvt_pk_bf16_f32 v132, v144, s0
	s_nop 0
	v_addc_co_u32_e32 v131, vcc, 0, v147, vcc
	global_store_short v[130:131], v132, off
	v_add_co_u32_e32 v130, vcc, 0x3cbb000, v146
	v_cvt_pk_bf16_f32 v132, v145, s0
	s_nop 0
	v_addc_co_u32_e32 v131, vcc, 0, v147, vcc
	global_store_short v[130:131], v132, off
	s_waitcnt vmcnt(32)
	s_waitcnt lgkmcnt(0)
	s_barrier
	s_cbranch_scc1 .LBB0_1375
	s_mov_b32 m0, s55
	v_lshl_add_u64 v[130:131], v[188:189], 0, s[10:11]
	global_load_lds_dwordx4 v[130:131], off
	v_lshl_add_u64 v[130:131], v[190:191], 0, s[10:11]
	s_mov_b32 m0, s58
	s_mul_hi_i32 s35, s69, 0x1800
	s_mul_i32 s34, s69, 0x1800
	global_load_lds_dwordx4 v[130:131], off
	v_lshl_add_u64 v[130:131], v[192:193], 0, s[10:11]
	s_mov_b32 m0, s59
	s_or_b64 s[34:35], s[34:35], s[0:1]
	global_load_lds_dwordx4 v[130:131], off
	v_lshl_add_u64 v[130:131], v[194:195], 0, s[10:11]
	s_mov_b32 m0, s62
	s_lshl_b64 s[34:35], s[34:35], 1
	s_and_b32 s23, s21, 0x8000
	global_load_lds_dwordx4 v[130:131], off
	v_lshl_add_u64 v[130:131], v[188:189], 0, s[12:13]
	s_mov_b32 m0, s63
	s_bitset1_b32 s34, 12
	s_add_i32 s23, s23, 0
	global_load_lds_dwordx4 v[130:131], off
	v_lshl_add_u64 v[130:131], v[172:173], 0, s[34:35]
	s_add_i32 s23, s23, 0x12000
	v_lshl_add_u64 v[132:133], v[130:131], 0, s[24:25]
	s_add_i32 m0, s23, s20
	s_nop 0
	global_load_lds_dwordx4 v[132:133], off nt
	v_lshl_add_u64 v[132:133], v[130:131], 0, s[26:27]
	s_add_i32 m0, s23, s65
	s_nop 0
	global_load_lds_dwordx4 v[132:133], off nt
	v_lshl_add_u64 v[132:133], v[130:131], 0, s[28:29]
	s_add_i32 m0, s23, s66
	v_lshl_add_u64 v[130:131], v[130:131], 0, s[30:31]
	global_load_lds_dwordx4 v[132:133], off nt
	s_add_i32 m0, s23, s67
	s_nop 0
	global_load_lds_dwordx4 v[130:131], off nt
	s_branch .LBB0_1375
